# UKV epilogue alignment + K-path deferred stores + UQ tiles on WGs 128-255, conv rows uniform again
# speedup vs baseline: 1.0078x; 1.0021x over previous
; __device__ __forceinline__ int ltid() { int t = threadIdx.x; asm volatile("" : "+v"(t)); return t; }
; __device__ __forceinline__ int lbid() { int t = blockIdx.x; asm volatile("" : "+s"(t)); return t; }
; __device__ __forceinline__ void conv_mixer_rows(CArgs a, int layer, int G) {
;     const int lane = ltid() & 63, wave = ltid() >> 6;
;     const int gw = lbid() * NWAVES + wave, NGW = G * NWAVES;
;     const unsigned char* WSB = a->ws;
;     const bf16_t* U = (const bf16_t*)(a->ws + WS_U); bf16_t* Y = (bf16_t*)(a->ws + WS_Y);
;     const float* cw = a->conv_w + (size_t)layer * 3 * 512;
;     const int c0 = lane * 8;
;     float w[3][8];
; #pragma unroll
;     for (int k = 0; k < 3; ++k) { const f32x4 a0 = *(const f32x4*)(cw + k * 512 + c0), a1 = *(const f32x4*)(cw + k * 512 + c0 + 4);
;         w[k][0] = a0[0]; w[k][1] = a0[1]; w[k][2] = a0[2]; w[k][3] = a0[3]; w[k][4] = a1[0]; w[k][5] = a1[1]; w[k][6] = a1[2]; w[k][7] = a1[3]; }
;     auto load = [&](int row, u32x4 (&raw)[7]) {
;         const int s = row & (SEQ - 1);
; #pragma unroll
;         for (int k = 0; k < 3; ++k) {
;             const int sp = s + k - 1; const int rr = (sp >= 0 && sp < SEQ) ? row + k - 1 : row;
;             const bf16_t* ur = U + (size_t)rr * NU;
;             u32x4 h = *(const u32x4*)(ur + UCH + c0), c = *(const u32x4*)(ur + UCC + c0);
;             if (!(sp >= 0 && sp < SEQ)) { h = (u32x4){0u, 0u, 0u, 0u}; c = (u32x4){0u, 0u, 0u, 0u}; }
;             raw[2 * k] = h; raw[2 * k + 1] = c;
;         }
;         raw[6] = *(const u32x4*)(U + (size_t)row * NU + UCB + c0);
;     ...
;     for (int row = gw; row < T; row += 2 * NGW) {
;         const int row2 = row + NGW;
;         u32x4 ra[7], rb[7];
;         load(row, ra);
;         if (row2 < T) load(row2, rb);
.Lp4_conv_entry:
	s_load_dwordx2 s[60:61], s[6:7], 0xe8
	s_load_dwordx2 s[12:13], s[6:7], 0xa8
	v_readfirstlane_b32 s10, v244
	v_and_b32_e32 v2, 63, v244
	v_lshlrev_b32_e32 v6, 5, v2
	v_lshlrev_b32_e32 v2, 4, v2
	v_add_u32_e32 v3, 0x2000, v2
	v_add_u32_e32 v4, 0x1c00, v2
	v_add_u32_e32 v5, 0xc00, v2
	v_add_u32_e32 v2, 0x1800, v2
	v_readlane_b32 s17, v253, 0
	s_lshr_b32 s10, s10, 6
	s_lshl_b32 s16, s64, 3
.Lcvm_map:
	s_lshl_b32 s17, s17, 3
	s_add_i32 s10, s10, s17
	s_mul_i32 s17, s8, 0x1800
	s_waitcnt lgkmcnt(0)
	s_and_b32 s61, s61, 0xffff
	s_add_u32 s12, s12, s17
	s_addc_u32 s13, s13, 0
	s_cmp_lt_u32 s10, 0x4000
	s_cbranch_scc0 .Lcvm_done
	global_load_dwordx4 v[8:11], v6, s[12:13]
	global_load_dwordx4 v[12:15], v6, s[12:13] offset:16
	global_load_dwordx4 v[16:19], v6, s[12:13] offset:2048
	global_load_dwordx4 v[20:23], v6, s[12:13] offset:2064
	s_add_u32 s12, s12, 0x1000
	s_addc_u32 s13, s13, 0
	global_load_dwordx4 v[24:27], v6, s[12:13]
	global_load_dwordx4 v[28:31], v6, s[12:13] offset:16
	s_and_b32 s21, s10, 0x7ff
	s_mul_i32 s19, s10, 0x2400
	s_add_u32 s19, s19, 0x3a00000
	s_sub_u32 s18, s19, 0x2400
	s_add_u32 s20, s19, 0x2400
	s_cmp_eq_u32 s21, 0
	s_cselect_b32 s18, s19, s18
	s_cmpk_eq_u32 s21, 0x7ff
	s_cselect_b32 s20, s19, s20
	buffer_load_dwordx4 v[32:35], v2, s[60:63], s18 offen
	buffer_load_dwordx4 v[36:39], v3, s[60:63], s18 offen
	buffer_load_dwordx4 v[40:43], v2, s[60:63], s19 offen
	buffer_load_dwordx4 v[44:47], v3, s[60:63], s19 offen
	buffer_load_dwordx4 v[48:51], v4, s[60:63], s19 offen
	buffer_load_dwordx4 v[52:55], v2, s[60:63], s20 offen
	buffer_load_dwordx4 v[56:59], v3, s[60:63], s20 offen
	s_mul_i32 s17, s16, 1
	s_add_i32 s17, s10, s17
	s_cmp_lt_u32 s17, 0x4000
	s_cselect_b32 s17, s17, s10
	s_and_b32 s21, s17, 0x7ff
	s_mul_i32 s19, s17, 0x2400
	s_add_u32 s19, s19, 0x3a00000
	s_sub_u32 s18, s19, 0x2400
	s_add_u32 s20, s19, 0x2400
	s_cmp_eq_u32 s21, 0
	s_cselect_b32 s18, s19, s18
	s_cmpk_eq_u32 s21, 0x7ff
	s_cselect_b32 s20, s19, s20
	buffer_load_dwordx4 v[60:63], v2, s[60:63], s18 offen
	buffer_load_dwordx4 v[64:67], v3, s[60:63], s18 offen
	buffer_load_dwordx4 v[68:71], v2, s[60:63], s19 offen
	buffer_load_dwordx4 v[72:75], v3, s[60:63], s19 offen
	buffer_load_dwordx4 v[76:79], v4, s[60:63], s19 offen
	buffer_load_dwordx4 v[80:83], v2, s[60:63], s20 offen
	buffer_load_dwordx4 v[84:87], v3, s[60:63], s20 offen
	s_mul_i32 s17, s16, 2
	s_add_i32 s17, s10, s17
	s_cmp_lt_u32 s17, 0x4000
	s_cselect_b32 s17, s17, s10
	s_and_b32 s21, s17, 0x7ff
	s_mul_i32 s19, s17, 0x2400
	s_add_u32 s19, s19, 0x3a00000
	s_sub_u32 s18, s19, 0x2400
	s_add_u32 s20, s19, 0x2400
	s_cmp_eq_u32 s21, 0
	s_cselect_b32 s18, s19, s18
	s_cmpk_eq_u32 s21, 0x7ff
	s_cselect_b32 s20, s19, s20
	buffer_load_dwordx4 v[88:91], v2, s[60:63], s18 offen
	buffer_load_dwordx4 v[92:95], v3, s[60:63], s18 offen
	buffer_load_dwordx4 v[96:99], v2, s[60:63], s19 offen
	buffer_load_dwordx4 v[100:103], v3, s[60:63], s19 offen
	buffer_load_dwordx4 v[104:107], v4, s[60:63], s19 offen
	buffer_load_dwordx4 v[108:111], v2, s[60:63], s20 offen
	buffer_load_dwordx4 v[112:115], v3, s[60:63], s20 offen
	s_waitcnt vmcnt(14)
	s_and_b32 s21, s10, 0x7ff
	s_cmp_lg_u32 s21, 0
	s_cbranch_scc1 .Lcvm_nz0_1
	v_mov_b32_e32 v32, 0
	v_mov_b32_e32 v33, 0
	v_mov_b32_e32 v34, 0
	v_mov_b32_e32 v35, 0
